# speedup vs baseline: 1.0018x; 1.0018x over previous
.LBB0_792:
	ds_read_b128 v[92:95], v233 offset:58112
	ds_read_b128 v[98:101], v233 offset:58128
	ds_read_b128 v[140:143], v233 offset:58368
	ds_read_b128 v[144:147], v233 offset:58384
	ds_read_b128 v[148:151], v233 offset:57344
	ds_read_b128 v[152:155], v233 offset:57360
	ds_read_b128 v[156:159], v233 offset:57600
	ds_read_b128 v[160:163], v233 offset:57616
	ds_read_b128 v[164:167], v233 offset:57856
	ds_read_b128 v[168:171], v233 offset:57872
	ds_read_b128 v[196:199], v233 offset:58624
	ds_read_b128 v[200:203], v233 offset:58640
	s_waitcnt vmcnt(1)
	v_lshlrev_b32_e32 v102, 16, v72
	v_lshlrev_b32_e32 v103, 16, v76
	v_lshlrev_b32_e32 v120, 16, v68
	v_add_f32_e32 v102, v103, v102
	v_and_b32_e32 v104, 0xffff0000, v76
	v_and_b32_e32 v105, 0xffff0000, v72
	v_fma_f32 v102, v102, 0.5, -v120
	v_and_b32_e32 v119, 0xffff0000, v68
	s_waitcnt lgkmcnt(11)
	v_fmac_f32_e32 v120, v102, v92
	v_add_f32_e32 v92, v104, v105
	v_lshlrev_b32_e32 v106, 16, v73
	v_lshlrev_b32_e32 v107, 16, v77
	v_fma_f32 v92, v92, 0.5, -v119
	v_lshlrev_b32_e32 v118, 16, v69
	v_fmac_f32_e32 v119, v92, v93
	v_add_f32_e32 v92, v107, v106
	v_and_b32_e32 v108, 0xffff0000, v77
	v_and_b32_e32 v109, 0xffff0000, v73
	v_fma_f32 v92, v92, 0.5, -v118
	v_and_b32_e32 v117, 0xffff0000, v69
	v_fmac_f32_e32 v118, v92, v94
	v_add_f32_e32 v92, v108, v109
	v_lshlrev_b32_e32 v110, 16, v74
	v_lshlrev_b32_e32 v111, 16, v78
	v_fma_f32 v92, v92, 0.5, -v117
	v_lshlrev_b32_e32 v116, 16, v70
	v_fmac_f32_e32 v117, v92, v95
	v_add_f32_e32 v92, v111, v110
	v_and_b32_e32 v112, 0xffff0000, v78
	v_and_b32_e32 v113, 0xffff0000, v74
	v_fma_f32 v92, v92, 0.5, -v116
	v_and_b32_e32 v115, 0xffff0000, v70
	s_waitcnt lgkmcnt(10)
	v_fmac_f32_e32 v116, v92, v98
	v_add_f32_e32 v92, v112, v113
	v_lshlrev_b32_e32 v121, 16, v75
	v_lshlrev_b32_e32 v122, 16, v79
	v_fma_f32 v92, v92, 0.5, -v115
	v_lshlrev_b32_e32 v114, 16, v71
	v_fmac_f32_e32 v115, v92, v99
	v_add_f32_e32 v92, v122, v121
	v_and_b32_e32 v123, 0xffff0000, v79
	v_and_b32_e32 v124, 0xffff0000, v75
	v_fma_f32 v92, v92, 0.5, -v114
	v_and_b32_e32 v97, 0xffff0000, v71
	v_fmac_f32_e32 v114, v92, v100
	v_add_f32_e32 v92, v123, v124
	v_fma_f32 v92, v92, 0.5, -v97
	v_fmac_f32_e32 v97, v92, v101
	s_waitcnt vmcnt(0)
	v_lshlrev_b32_e32 v100, 16, v84
	v_and_b32_e32 v101, 0xffff0000, v84
	v_lshlrev_b32_e32 v102, 16, v88
	v_and_b32_e32 v103, 0xffff0000, v88
	v_lshlrev_b32_e32 v98, 16, v80
	v_and_b32_e32 v99, 0xffff0000, v80
	v_pk_add_f32 v[100:101], v[100:101], v[102:103]
	v_lshlrev_b32_e32 v102, 16, v90
	v_pk_fma_f32 v[100:101], v[100:101], 0.5, v[98:99] op_sel_hi:[1,0,1] neg_lo:[0,0,1] neg_hi:[0,0,1]
	v_and_b32_e32 v103, 0xffff0000, v90
	s_waitcnt lgkmcnt(9)
	v_pk_fma_f32 v[106:107], v[100:101], v[140:141], v[98:99]
	v_lshlrev_b32_e32 v98, 16, v85
	v_and_b32_e32 v99, 0xffff0000, v85
	v_lshlrev_b32_e32 v100, 16, v89
	v_and_b32_e32 v101, 0xffff0000, v89
	v_lshlrev_b32_e32 v92, 16, v81
	v_and_b32_e32 v93, 0xffff0000, v81
	v_pk_add_f32 v[98:99], v[98:99], v[100:101]
	v_lshlrev_b32_e32 v100, 16, v86
	v_pk_fma_f32 v[98:99], v[98:99], 0.5, v[92:93] op_sel_hi:[1,0,1] neg_lo:[0,0,1] neg_hi:[0,0,1]
	v_and_b32_e32 v101, 0xffff0000, v86
	v_pk_fma_f32 v[108:109], v[98:99], v[142:143], v[92:93]
	v_lshlrev_b32_e32 v98, 16, v82
	v_and_b32_e32 v99, 0xffff0000, v82
	v_pk_add_f32 v[100:101], v[100:101], v[102:103]
	v_lshlrev_b32_e32 v104, 16, v36
	v_pk_fma_f32 v[100:101], v[100:101], 0.5, v[98:99] op_sel_hi:[1,0,1] neg_lo:[0,0,1] neg_hi:[0,0,1]
	v_and_b32_e32 v105, 0xffff0000, v36
	s_waitcnt lgkmcnt(8)
	v_pk_fma_f32 v[110:111], v[100:101], v[144:145], v[98:99]
	v_lshlrev_b32_e32 v98, 16, v87
	v_and_b32_e32 v99, 0xffff0000, v87
	v_lshlrev_b32_e32 v100, 16, v91
	v_and_b32_e32 v101, 0xffff0000, v91
	v_lshlrev_b32_e32 v92, 16, v83
	v_and_b32_e32 v93, 0xffff0000, v83
	v_pk_add_f32 v[98:99], v[98:99], v[100:101]
	v_lshlrev_b32_e32 v122, 16, v40
	v_pk_fma_f32 v[98:99], v[98:99], 0.5, v[92:93] op_sel_hi:[1,0,1] neg_lo:[0,0,1] neg_hi:[0,0,1]
	v_and_b32_e32 v123, 0xffff0000, v40
	v_pk_fma_f32 v[112:113], v[98:99], v[146:147], v[92:93]
	v_lshlrev_b32_e32 v102, 16, v32
	v_and_b32_e32 v103, 0xffff0000, v32
	v_pk_add_f32 v[104:105], v[104:105], v[122:123]
	v_lshlrev_b32_e32 v122, 16, v41
	v_pk_fma_f32 v[104:105], v[104:105], 0.5, v[102:103] op_sel_hi:[1,0,1] neg_lo:[0,0,1] neg_hi:[0,0,1]
	v_and_b32_e32 v123, 0xffff0000, v41
	s_waitcnt lgkmcnt(7)
	v_pk_fma_f32 v[92:93], v[104:105], v[148:149], v[102:103]
	v_lshlrev_b32_e32 v104, 16, v37
	v_and_b32_e32 v105, 0xffff0000, v37
	v_lshlrev_b32_e32 v102, 16, v33
	v_and_b32_e32 v103, 0xffff0000, v33
	v_pk_add_f32 v[104:105], v[104:105], v[122:123]
	v_lshlrev_b32_e32 v122, 16, v42
	v_pk_fma_f32 v[104:105], v[104:105], 0.5, v[102:103] op_sel_hi:[1,0,1] neg_lo:[0,0,1] neg_hi:[0,0,1]
	v_and_b32_e32 v123, 0xffff0000, v42
	v_pk_fma_f32 v[94:95], v[104:105], v[150:151], v[102:103]
	v_lshlrev_b32_e32 v104, 16, v38
	v_and_b32_e32 v105, 0xffff0000, v38
	v_lshlrev_b32_e32 v102, 16, v34
	v_and_b32_e32 v103, 0xffff0000, v34
	v_pk_add_f32 v[104:105], v[104:105], v[122:123]
	v_lshlrev_b32_e32 v122, 16, v43
	v_pk_fma_f32 v[104:105], v[104:105], 0.5, v[102:103] op_sel_hi:[1,0,1] neg_lo:[0,0,1] neg_hi:[0,0,1]
	v_and_b32_e32 v123, 0xffff0000, v43
	s_waitcnt lgkmcnt(6)
	v_pk_fma_f32 v[98:99], v[104:105], v[152:153], v[102:103]
	v_lshlrev_b32_e32 v104, 16, v39
	v_and_b32_e32 v105, 0xffff0000, v39
	v_lshlrev_b32_e32 v102, 16, v35
	v_and_b32_e32 v103, 0xffff0000, v35
	v_pk_add_f32 v[104:105], v[104:105], v[122:123]
	v_lshlrev_b32_e32 v124, 16, v48
	v_pk_fma_f32 v[104:105], v[104:105], 0.5, v[102:103] op_sel_hi:[1,0,1] neg_lo:[0,0,1] neg_hi:[0,0,1]
	v_and_b32_e32 v125, 0xffff0000, v48
	v_pk_fma_f32 v[100:101], v[104:105], v[154:155], v[102:103]
	v_lshlrev_b32_e32 v126, 16, v52
	v_and_b32_e32 v127, 0xffff0000, v52
	v_lshlrev_b32_e32 v122, 16, v44
	v_and_b32_e32 v123, 0xffff0000, v44
	v_pk_add_f32 v[124:125], v[124:125], v[126:127]
	v_lshlrev_b32_e32 v126, 16, v53
	v_pk_fma_f32 v[124:125], v[124:125], 0.5, v[122:123] op_sel_hi:[1,0,1] neg_lo:[0,0,1] neg_hi:[0,0,1]
	v_and_b32_e32 v127, 0xffff0000, v53
	s_waitcnt lgkmcnt(5)
	v_pk_fma_f32 v[102:103], v[124:125], v[156:157], v[122:123]
	v_lshlrev_b32_e32 v124, 16, v49
	v_and_b32_e32 v125, 0xffff0000, v49
	v_lshlrev_b32_e32 v122, 16, v45
	v_and_b32_e32 v123, 0xffff0000, v45
	v_pk_add_f32 v[124:125], v[124:125], v[126:127]
	v_lshlrev_b32_e32 v128, 16, v50
	v_pk_fma_f32 v[124:125], v[124:125], 0.5, v[122:123] op_sel_hi:[1,0,1] neg_lo:[0,0,1] neg_hi:[0,0,1]
	v_and_b32_e32 v129, 0xffff0000, v50
	v_pk_fma_f32 v[104:105], v[124:125], v[158:159], v[122:123]
	v_lshlrev_b32_e32 v130, 16, v54
	v_and_b32_e32 v131, 0xffff0000, v54
	v_lshlrev_b32_e32 v126, 16, v46
	v_and_b32_e32 v127, 0xffff0000, v46
	v_pk_add_f32 v[128:129], v[128:129], v[130:131]
	v_lshlrev_b32_e32 v130, 16, v55
	v_pk_fma_f32 v[128:129], v[128:129], 0.5, v[126:127] op_sel_hi:[1,0,1] neg_lo:[0,0,1] neg_hi:[0,0,1]
	v_and_b32_e32 v131, 0xffff0000, v55
	s_waitcnt lgkmcnt(4)
	v_pk_fma_f32 v[122:123], v[128:129], v[160:161], v[126:127]
	v_lshlrev_b32_e32 v128, 16, v51
	v_and_b32_e32 v129, 0xffff0000, v51
	v_lshlrev_b32_e32 v126, 16, v47
	v_and_b32_e32 v127, 0xffff0000, v47
	v_pk_add_f32 v[128:129], v[128:129], v[130:131]
	v_lshlrev_b32_e32 v132, 16, v60
	v_pk_fma_f32 v[128:129], v[128:129], 0.5, v[126:127] op_sel_hi:[1,0,1] neg_lo:[0,0,1] neg_hi:[0,0,1]
	v_and_b32_e32 v133, 0xffff0000, v60
	v_pk_fma_f32 v[124:125], v[128:129], v[162:163], v[126:127]
	v_lshlrev_b32_e32 v134, 16, v64
	v_and_b32_e32 v135, 0xffff0000, v64
	v_lshlrev_b32_e32 v130, 16, v56
	v_and_b32_e32 v131, 0xffff0000, v56
	v_pk_add_f32 v[132:133], v[132:133], v[134:135]
	v_lshlrev_b32_e32 v134, 16, v65
	v_pk_fma_f32 v[132:133], v[132:133], 0.5, v[130:131] op_sel_hi:[1,0,1] neg_lo:[0,0,1] neg_hi:[0,0,1]
	v_and_b32_e32 v135, 0xffff0000, v65
	s_waitcnt lgkmcnt(3)
	v_pk_fma_f32 v[126:127], v[132:133], v[164:165], v[130:131]
	v_lshlrev_b32_e32 v132, 16, v61
	v_and_b32_e32 v133, 0xffff0000, v61
	v_lshlrev_b32_e32 v130, 16, v57
	v_and_b32_e32 v131, 0xffff0000, v57
	v_pk_add_f32 v[132:133], v[132:133], v[134:135]
	v_lshlrev_b32_e32 v136, 16, v62
	v_pk_fma_f32 v[132:133], v[132:133], 0.5, v[130:131] op_sel_hi:[1,0,1] neg_lo:[0,0,1] neg_hi:[0,0,1]
	v_and_b32_e32 v137, 0xffff0000, v62
	v_pk_fma_f32 v[128:129], v[132:133], v[166:167], v[130:131]
	v_lshlrev_b32_e32 v138, 16, v66
	v_and_b32_e32 v139, 0xffff0000, v66
	v_lshlrev_b32_e32 v134, 16, v58
	v_and_b32_e32 v135, 0xffff0000, v58
	v_pk_add_f32 v[136:137], v[136:137], v[138:139]
	v_lshlrev_b32_e32 v138, 16, v67
	v_pk_fma_f32 v[136:137], v[136:137], 0.5, v[134:135] op_sel_hi:[1,0,1] neg_lo:[0,0,1] neg_hi:[0,0,1]
	v_and_b32_e32 v139, 0xffff0000, v67
	s_waitcnt lgkmcnt(2)
	v_pk_fma_f32 v[130:131], v[136:137], v[168:169], v[134:135]
	v_lshlrev_b32_e32 v136, 16, v63
	v_and_b32_e32 v137, 0xffff0000, v63
	v_lshlrev_b32_e32 v134, 16, v59
	v_and_b32_e32 v135, 0xffff0000, v59
	v_pk_add_f32 v[136:137], v[136:137], v[138:139]
	v_add_f32_e32 v97, v97, v97
	v_pk_fma_f32 v[136:137], v[136:137], 0.5, v[134:135] op_sel_hi:[1,0,1] neg_lo:[0,0,1] neg_hi:[0,0,1]
	v_mul_f32_e32 v97, 0x3fb8aa3b, v97
	v_pk_fma_f32 v[132:133], v[136:137], v[170:171], v[134:135]
	ds_write_b128 v234, v[92:95]
	ds_write_b128 v234, v[98:101] offset:16
	ds_write_b128 v234, v[102:105] offset:8192
	ds_write_b128 v234, v[122:125] offset:8208
	ds_write_b128 v234, v[126:129] offset:16384
	ds_write_b128 v234, v[130:133] offset:16400
	v_exp_f32_e32 v97, v97
	s_cmp_eq_u32 s37, 0
	s_waitcnt lgkmcnt(7)
	v_pk_mul_f32 v[92:93], v[102:103], v[196:197]
	s_nop 0
	v_pk_mul_f32 v[102:103], v[92:93], v[92:93]
	v_pk_mul_f32 v[94:95], v[104:105], v[198:199]
	v_add_f32_e32 v102, v102, v103
	v_pk_mul_f32 v[104:105], v[94:95], v[94:95]
	s_waitcnt lgkmcnt(6)
	v_pk_mul_f32 v[98:99], v[122:123], v[200:201]
	v_add_f32_e32 v102, v102, v104
	v_pk_mul_f32 v[122:123], v[98:99], v[98:99]
	v_add_f32_e32 v102, v102, v105
	v_pk_mul_f32 v[100:101], v[124:125], v[202:203]
	v_add_f32_e32 v102, v102, v122
	v_pk_mul_f32 v[124:125], v[100:101], v[100:101]
	v_add_f32_e32 v102, v102, v123
	v_add_f32_e32 v102, v102, v124
	v_add_f32_e32 v102, v102, v125
	v_add_f32_e32 v97, 1.0, v97
	s_nop 0
	v_add_f32_dpp v102, v102, v102 quad_perm:[1,0,3,2] row_mask:0xf bank_mask:0xf bound_ctrl:1
	s_nop 1
	v_add_f32_dpp v102, v102, v102 quad_perm:[2,3,0,1] row_mask:0xf bank_mask:0xf bound_ctrl:1
	s_nop 1
	v_add_f32_dpp v102, v102, v102 row_half_mirror row_mask:0xf bank_mask:0xf bound_ctrl:1
	v_add_f32_e32 v102, 0x2b8cbccc, v102
	v_cmp_gt_f32_e64 s[0:1], s33, v102
	v_mul_f32_e32 v103, 0x4b800000, v102
	s_nop 0
	v_cndmask_b32_e64 v102, v102, v103, s[0:1]
	v_rsq_f32_e32 v102, v102
	s_nop 0
	v_mul_f32_e32 v103, 0x45800000, v102
	v_cndmask_b32_e64 v102, v102, v103, s[0:1]
	v_pk_mul_f32 v[92:93], v[92:93], v[102:103] op_sel_hi:[1,0]
	v_pk_mul_f32 v[94:95], v[94:95], v[102:103] op_sel_hi:[1,0]
	ds_write_b128 v234, v[92:95] offset:24576
	v_pk_mul_f32 v[92:93], v[98:99], v[102:103] op_sel_hi:[1,0]
	v_pk_mul_f32 v[94:95], v[100:101], v[102:103] op_sel_hi:[1,0]
	ds_write_b128 v234, v[92:95] offset:24592
	v_add_f32_e32 v92, v120, v120
	v_add_f32_e32 v93, v119, v119
	v_add_f32_e32 v94, v118, v118
	v_add_f32_e32 v95, v117, v117
	v_add_f32_e32 v98, v116, v116
	v_add_f32_e32 v99, v115, v115
	v_add_f32_e32 v100, v114, v114
	v_mul_f32_e32 v92, 0x3fb8aa3b, v92
	v_mul_f32_e32 v93, 0x3fb8aa3b, v93
	v_mul_f32_e32 v94, 0x3fb8aa3b, v94
	v_mul_f32_e32 v95, 0x3fb8aa3b, v95
	v_mul_f32_e32 v98, 0x3fb8aa3b, v98
	v_mul_f32_e32 v99, 0x3fb8aa3b, v99
	v_mul_f32_e32 v100, 0x3fb8aa3b, v100
	v_exp_f32_e32 v92, v92
	v_exp_f32_e32 v93, v93
	v_exp_f32_e32 v94, v94
	v_exp_f32_e32 v95, v95
	v_exp_f32_e32 v98, v98
	v_exp_f32_e32 v99, v99
	v_exp_f32_e32 v100, v100
	v_add_f32_e32 v92, 1.0, v92
	v_add_f32_e32 v93, 1.0, v93
	v_add_f32_e32 v94, 1.0, v94
	v_add_f32_e32 v95, 1.0, v95
	v_add_f32_e32 v98, 1.0, v98
	v_add_f32_e32 v99, 1.0, v99
	v_add_f32_e32 v100, 1.0, v100
	v_rcp_f32_e32 v92, v92
	v_rcp_f32_e32 v93, v93
	v_rcp_f32_e32 v94, v94
	v_rcp_f32_e32 v95, v95
	v_rcp_f32_e32 v98, v98
	v_rcp_f32_e32 v99, v99
	v_rcp_f32_e32 v100, v100
	v_rcp_f32_e32 v101, v97
	v_pk_fma_f32 v[92:93], v[92:93], 2.0, 1.0 op_sel_hi:[1,0,0] neg_lo:[1,0,0] neg_hi:[1,0,0]
	v_pk_fma_f32 v[94:95], v[94:95], 2.0, 1.0 op_sel_hi:[1,0,0] neg_lo:[1,0,0] neg_hi:[1,0,0]
	v_pk_fma_f32 v[98:99], v[98:99], 2.0, 1.0 op_sel_hi:[1,0,0] neg_lo:[1,0,0] neg_hi:[1,0,0]
	v_pk_fma_f32 v[100:101], v[100:101], 2.0, 1.0 op_sel_hi:[1,0,0] neg_lo:[1,0,0] neg_hi:[1,0,0]
	v_cvt_pk_bf16_f32 v92, v92, v93
	v_cvt_pk_bf16_f32 v93, v94, v95
	v_cvt_pk_bf16_f32 v94, v98, v99
	v_cvt_pk_bf16_f32 v95, v100, v101
	ds_write_b128 v235, v[92:95] offset:49152
	v_cvt_pk_bf16_f32 v92, v106, v107
	v_cvt_pk_bf16_f32 v93, v108, v109
	v_cvt_pk_bf16_f32 v94, v110, v111
	v_cvt_pk_bf16_f32 v95, v112, v113
	ds_write_b128 v235, v[92:95] offset:53248
	s_waitcnt lgkmcnt(0)
	s_barrier
	s_cbranch_scc1 .LBB0_794
	v_lshl_add_u32 v92, s37, 5, v237
	v_xad_u32 v93, v92, -1, s47
	v_cndmask_b32_e32 v102, v93, v92, vcc
	ds_read_b128 v[92:95], v238 offset:58880
	ds_read_b128 v[98:101], v238 offset:58896
	v_ashrrev_i32_e32 v103, 31, v102
	s_waitcnt lgkmcnt(1)
	v_cvt_pk_bf16_f32 v92, v92, v93
	v_cvt_pk_bf16_f32 v93, v94, v95
	s_waitcnt lgkmcnt(0)
	v_cvt_pk_bf16_f32 v94, v98, v99
	v_lshl_add_u64 v[98:99], s[80:81], 0, v[102:103]
	v_lshlrev_b64 v[98:99], 10, v[98:99]
	v_cvt_pk_bf16_f32 v95, v100, v101
	v_lshl_add_u64 v[98:99], v[190:191], 0, v[98:99]
	global_store_dwordx4 v[98:99], v[92:95], off
